# v041 stack + weight conversion moved from the layer-0 mixer phase into the idle 7-unit workgroups of the two GEMM1 phases (tail fill)
# speedup vs baseline: 1.0114x; 1.0114x over previous
; #define LAS __attribute__((address_space(3)))
; template <class A> __device__ __forceinline__ void p0_convert(const A& a, LAS unsigned char* lds, int gw, int NGW, int wave, int lane, const int g_lo, const int g_hi, const bool small) {
;     LAS float* scr = (LAS float*)(lds + wave * 8448);
;     constexpr int I_IN = (D / 64) * (INW / 32), I_OA = (512 / 64) * (D / 32), I_OUT = (D / 64) * (D / 32), I_UP = (D / 64) * (NUP / 32), I_DN = (DFF / 64) * (D / 32);
;     constexpr int PER_L = I_IN + 2 * I_OA + I_OUT + I_UP + I_DN;
;     for (int it = g_lo + gw; it < g_hi; it += NGW) {
;         const int l = it / PER_L; int r = it % PER_L; unsigned char* wl = a.ws + (size_t)l * LSTRIDE;
; __global__ void __launch_bounds__(NWAVES * 64, 2) fwd_kernel(Args args) {
;     ...
;         if ((PHM & 1) && rep == 0 && (ph == 0 || ph == 2)) {
;             constexpr int CV_IN = (D / 64) * (INW / 32), CV_ALL = 2 * (CV_IN + 2 * ((512 / 64) * (D / 32)) + (D / 64) * (D / 32) + (D / 64) * (NUP / 32) + (DFF / 64) * (D / 32));
;             __syncthreads();
;             p0_convert(a, lds, gw, NGW, wave, lane, ph == 0 ? 0 : CV_IN, ph == 0 ? CV_IN : CV_ALL, ph == 0);
.LBB0_378:
	s_andn2_b64 vcc, exec, s[18:19]
	s_cbranch_vccnz cvx_check
	v_readlane_b32 s2, v254, 59
	v_readlane_b32 s3, v254, 60
	s_and_b64 s[2:3], s[2:3], exec
	s_movk_i32 s2, 0x2380
	v_readlane_b32 s18, v254, 61
	s_cselect_b32 s3, 0, 0x1c00
	s_cselect_b32 s2, 0x780, s2
	s_ashr_i32 s18, s18, 6
	s_lshl_b32 s19, s21, 3
	s_add_i32 s26, s18, s19
	s_add_i32 s3, s26, s3
cvx_enter:
	s_cmp_ge_i32 s3, s2
	s_waitcnt lgkmcnt(0)
	s_barrier
	s_cbranch_scc1 .LBB0_414
	s_mulk_i32 s18, 0x2100
	v_lshrrev_b32_e32 v1, 5, v241
	v_and_b32_e32 v0, 31, v242
	s_add_i32 s18, s18, 0
	v_lshlrev_b32_e32 v4, 2, v0
	v_mul_u32_u24_e32 v5, 0x84, v1
	v_add3_u32 v71, s18, v4, v5
	v_lshlrev_b32_e32 v4, 3, v241
	v_lshrrev_b32_e32 v72, 3, v241
	v_and_b32_e32 v8, 56, v4
	v_mul_u32_u24_e32 v4, 0x84, v8
	v_lshlrev_b32_e32 v5, 2, v72
	v_add3_u32 v73, s18, v4, v5
	s_lshl_b32 s18, s3, 5
	s_add_i32 s21, s18, 0xfffed000
	s_lshl_b32 s18, s3, 1
	v_or_b32_e32 v3, 0x800, v0
	v_or_b32_e32 v9, 0x1000, v0
	v_or_b32_e32 v42, 0x1800, v0
	v_or_b32_e32 v43, 0x2000, v0
	v_or_b32_e32 v44, 0x2800, v0
	v_or_b32_e32 v45, 0x3000, v0
	v_or_b32_e32 v46, 0x3800, v0
	v_or_b32_e32 v47, 0x4000, v0
	v_or_b32_e32 v48, 0x4800, v0
	v_or_b32_e32 v49, 0x5000, v0
	v_or_b32_e32 v50, 0x5800, v0
	v_or_b32_e32 v51, 0x6000, v0
	v_or_b32_e32 v52, 0x6800, v0
	v_or_b32_e32 v53, 0x7000, v0
	v_or_b32_e32 v54, 0x7800, v0
	v_or_b32_e32 v55, 0x8000, v0
	v_or_b32_e32 v56, 0x8800, v0
	v_or_b32_e32 v57, 0x9000, v0
	v_or_b32_e32 v58, 0x9800, v0
	v_or_b32_e32 v59, 0xa000, v0
	v_or_b32_e32 v60, 0xa800, v0
	v_or_b32_e32 v61, 0xb000, v0
	v_or_b32_e32 v62, 0xb800, v0
	v_or_b32_e32 v63, 0xc000, v0
	v_or_b32_e32 v64, 0xc800, v0
	v_or_b32_e32 v65, 0xd000, v0
	v_or_b32_e32 v66, 0xd800, v0
	v_or_b32_e32 v67, 0xe000, v0
	v_or_b32_e32 v68, 0xe800, v0
	v_or_b32_e32 v69, 0xf000, v0
	v_or_b32_e32 v70, 0xf800, v0
	v_or_b32_e32 v74, 8, v72
	v_or_b32_e32 v75, 16, v72
	v_or_b32_e32 v76, 24, v72
	s_lshl_b32 s23, s20, 5
	s_add_i32 s24, s18, 0xffffed00
	s_lshl_b32 s25, s20, 1
	s_branch .LBB0_383

; template <class A> __device__ __forceinline__ void p0_convert(const A& a, LAS unsigned char* lds, int gw, int NGW, int wave, int lane, const int g_lo, const int g_hi, const bool small) {
;     ...
;     if (small) for (int e = gw * 64 + lane; e < 2 * 4 * NUP; e += NGW * 64) { const int l = e / (4 * NUP), k = (e / NUP) & 3, c = e % NUP;
; __global__ void __launch_bounds__(NWAVES * 64, 2) fwd_kernel(Args args) {
;     ...
;             p0_convert(a, lds, gw, NGW, wave, lane, ph == 0 ? 0 : CV_IN, ph == 0 ? CV_IN : CV_ALL, ph == 0);
cvx_check:
	s_cmpk_lt_u32 s89, 0x80
	s_cbranch_scc1 .LBB0_430
	s_cmp_eq_u32 s10, 1
	s_cbranch_scc1 cvx_l0
	s_cmp_eq_u32 s10, 8
	s_cbranch_scc0 .LBB0_430
	s_movk_i32 s3, 0x2380
	s_movk_i32 s2, 0x3800
	s_branch cvx_set
cvx_l0:
	s_movk_i32 s3, 0x780
	s_movk_i32 s2, 0x1c00
cvx_set:
	v_readlane_b32 s18, v254, 61
	s_lshr_b32 s20, s20, 1
	s_sub_i32 s19, s89, 0x80
	s_lshl_b32 s19, s19, 3
	s_ashr_i32 s18, s18, 6
	s_add_i32 s26, s18, s19
	s_add_i32 s3, s26, s3
	s_waitcnt vmcnt(0)
	s_branch cvx_enter
.LBB0_414:
	s_lshl_b32 s20, s12, 3
	v_readlane_b32 s2, v254, 59
	v_readlane_b32 s3, v254, 60
	s_and_b64 vcc, exec, s[2:3]
	s_cbranch_vccz .LBB0_430
	v_lshl_or_b32 v0, s26, 6, v241
	s_mov_b32 s2, 0xb000
	v_cmp_gt_i32_e32 vcc, s2, v0
	s_and_saveexec_b64 s[18:19], vcc
	s_mov_b32 s21, 0x2e8ba2e9
	s_cbranch_execz .LBB0_422
	s_mov_b64 s[34:35], 0
	v_mov_b32_e32 v4, v0
	s_branch .LBB0_418
